# decode-row epilogues of w_o and down: residual and gain loads issued before the exchange polls
# speedup vs baseline: 1.0373x; 1.0002x over previous
.LBB0_876:
	s_or_b64 exec, exec, s[24:25]
	v_lshl_or_b32 v230, s16, 5, v0
	v_lshl_or_b32 v232, s40, 4, v1
	v_ashrrev_i32_e32 v231, 31, v230
	v_lshlrev_b32_e32 v232, 12, v232
	v_mov_b32_e32 v233, v9
	v_readlane_b32 s42, v252, 16
	v_readlane_b32 s43, v252, 17
	v_readlane_b32 s50, v252, 24
	v_readlane_b32 s51, v252, 25
	v_lshlrev_b64 v[234:235], 2, v[230:231]
	v_lshl_add_u64 v[232:233], s[42:43], 0, v[232:233]
	v_lshl_add_u64 v[238:239], s[50:51], 0, v[234:235]
	v_lshl_add_u64 v[236:237], v[232:233], 0, v[234:235]
	global_load_dwordx4 v[200:203], v[236:237], off
	global_load_dwordx4 v[204:207], v[238:239], off
	global_load_dwordx4 v[208:211], v[238:239], off offset:16
	global_load_dwordx4 v[212:215], v[236:237], off offset:16
	v_lshlrev_b32_e32 v8, 3, v12
	v_lshl_add_u64 v[28:29], s[0:1], 0, v[8:9]
	v_lshlrev_b32_e32 v18, 3, v0
	v_mov_b32_e32 v19, v9
	s_lshl_b32 s17, s40, 9
	v_lshl_add_u64 v[28:29], v[28:29], 0, v[18:19]
	v_mov_b32_e32 v17, 0
	s_mov_b64 s[0:1], 0
	s_branch .LBB0_879

.LBB0_940:
	s_or_b64 exec, exec, s[0:1]
	v_lshl_or_b32 v30, s16, 5, v0
	v_lshl_or_b32 v28, s40, 4, v1
	v_readlane_b32 s40, v252, 14
	v_ashrrev_i32_e32 v31, 31, v30
	v_lshlrev_b32_e32 v44, 12, v28
	v_mov_b32_e32 v45, v9
	v_readlane_b32 s42, v252, 16
	v_readlane_b32 s43, v252, 17
	v_readlane_b32 s50, v252, 24
	v_readlane_b32 s51, v252, 25
	v_lshl_add_u64 v[44:45], s[42:43], 0, v[44:45]
	v_lshlrev_b64 v[46:47], 2, v[30:31]
	v_lshl_add_u64 v[56:57], v[44:45], 0, v[46:47]
	v_lshl_add_u64 v[52:53], s[50:51], 0, v[46:47]
	s_nop 0
	s_nop 0
	v_add_f32_e32 v14, 0, v14
	v_add_f32_e32 v14, v14, v17
	v_add_f32_e32 v14, v14, v19
	v_add_f32_e32 v14, v14, v39
	v_add_f32_e32 v14, v14, v40
	v_add_f32_e32 v14, v14, v41
	v_add_f32_e32 v14, v14, v42
	v_add_f32_e32 v14, v14, v43
	ds_bpermute_b32 v17, v37, v14
	v_readlane_b32 s41, v252, 15
	v_readlane_b32 s44, v252, 18
	v_readlane_b32 s45, v252, 19
	v_readlane_b32 s46, v252, 20
	s_waitcnt lgkmcnt(0)
	v_add_f32_e32 v14, v14, v17
	ds_bpermute_b32 v17, v38, v14
	v_readlane_b32 s47, v252, 21
	v_readlane_b32 s40, v252, 0
	v_readlane_b32 s44, v252, 4
	v_readlane_b32 s45, v252, 5
	s_waitcnt lgkmcnt(0)
	v_add_f32_e32 v14, v14, v17
	v_fmamk_f32 v14, v14, 0x3a800000, v35
	v_mul_f32_e32 v17, 0x4f800000, v14
	v_cmp_gt_f32_e32 vcc, s35, v14
	v_readlane_b32 s46, v252, 6
	v_readlane_b32 s47, v252, 7
	v_cndmask_b32_e32 v14, v14, v17, vcc
	v_sqrt_f32_e32 v17, v14
	s_mov_b64 s[24:25], s[44:45]
	v_mov_b32_e32 v41, v9
	v_lshlrev_b32_e32 v40, 11, v28
	v_add_u32_e32 v19, -1, v17
	v_add_u32_e32 v29, 1, v17
	v_fma_f32 v39, -v19, v17, v14
	v_fma_f32 v42, -v29, v17, v14
	v_cmp_ge_f32_e64 s[0:1], 0, v39
	s_mov_b64 s[26:27], s[46:47]
	v_lshl_add_u64 v[40:41], s[26:27], 0, v[40:41]
	v_cndmask_b32_e64 v17, v17, v19, s[0:1]
	v_cmp_lt_f32_e64 s[0:1], 0, v42
	v_lshl_add_u64 v[30:31], v[30:31], 1, v[40:41]
	v_readlane_b32 s48, v252, 22
	v_cndmask_b32_e64 v17, v17, v29, s[0:1]
	v_mul_f32_e32 v19, 0x37800000, v17
	v_cndmask_b32_e32 v17, v17, v19, vcc
	v_cmp_class_f32_e32 vcc, v14, v36
	v_readlane_b32 s49, v252, 23
	v_readlane_b32 s52, v252, 26
	v_cndmask_b32_e32 v14, v17, v14, vcc
	v_div_scale_f32 v17, s[0:1], v14, v14, 1.0
	v_rcp_f32_e32 v19, v17
	v_div_scale_f32 v29, vcc, 1.0, v14, 1.0
	s_lshl_b32 s0, s17, 3
	v_fma_f32 v39, -v17, v19, 1.0
	v_fmac_f32_e32 v19, v39, v19
	v_mul_f32_e32 v39, v29, v19
	v_fma_f32 v40, -v17, v39, v29
	v_fmac_f32_e32 v39, v40, v19
	v_fma_f32 v17, -v17, v39, v29
	v_div_fmas_f32 v17, v17, v19, v39
	v_div_fixup_f32 v14, v17, v14, 1.0
	v_pk_mul_f32 v[24:25], v[24:25], v[14:15] op_sel_hi:[1,0]
	v_pk_mul_f32 v[20:21], v[20:21], v[14:15] op_sel_hi:[1,0]
	v_pk_mul_f32 v[26:27], v[26:27], v[14:15] op_sel_hi:[1,0]
	v_pk_mul_f32 v[22:23], v[22:23], v[14:15] op_sel_hi:[1,0]
	s_add_u32 s0, s26, s0
	s_addc_u32 s1, s27, 0
	s_add_u32 s0, s0, 0xe4a8000
	s_addc_u32 s1, s1, 0
	v_readlane_b32 s53, v252, 27
	v_readlane_b32 s54, v252, 28
	v_readlane_b32 s55, v252, 29
	v_readlane_b32 s41, v252, 1
	v_readlane_b32 s42, v252, 2
	v_readlane_b32 s43, v252, 3
	s_waitcnt vmcnt(0)
	v_pk_fma_f32 v[40:41], v[206:207], v[20:21], v[202:203]
	v_pk_fma_f32 v[24:25], v[204:205], v[24:25], v[200:201]
	s_waitcnt vmcnt(0)
	v_pk_fma_f32 v[42:43], v[210:211], v[22:23], v[214:215]
	v_pk_fma_f32 v[26:27], v[208:209], v[26:27], v[212:213]
	v_cvt_pk_bf16_f32 v20, v24, v25
	v_mul_f32_e32 v14, v25, v25
	v_mul_f32_e32 v17, v41, v41
	v_mul_f32_e32 v19, v27, v27
	v_mul_f32_e32 v25, v43, v43
	v_fmac_f32_e32 v14, v24, v24
	v_fmac_f32_e32 v17, v40, v40
	v_fmac_f32_e32 v19, v26, v26
	v_fmac_f32_e32 v25, v42, v42
	v_add_f32_e32 v14, v14, v17
	v_add_f32_e32 v17, v19, v25
	v_add_f32_e32 v14, v14, v17
	ds_bpermute_b32 v17, v37, v14
	v_add_co_u32_e32 v24, vcc, s36, v30
	v_cvt_pk_bf16_f32 v21, v40, v41
	v_cvt_pk_bf16_f32 v22, v26, v27
	s_waitcnt lgkmcnt(0)
	v_add_f32_e32 v14, v14, v17
	ds_bpermute_b32 v17, v38, v14
	v_addc_co_u32_e32 v25, vcc, 0, v31, vcc
	v_cvt_pk_bf16_f32 v23, v42, v43
	global_store_dwordx4 v[24:25], v[20:23], off sc0 sc1
	s_and_saveexec_b64 s[24:25], s[6:7]
	s_cbranch_execz .LBB0_942
	s_waitcnt lgkmcnt(0)
	v_add_f32_e32 v14, v14, v17
	v_mov_b32_e32 v17, v9
	v_lshl_add_u64 v[16:17], s[0:1], 0, v[16:17]
	s_ashr_i32 s17, s16, 31
	v_lshl_add_u64 v[16:17], s[16:17], 3, v[16:17]
	global_store_dwordx2 v[16:17], v[14:15], off sc1

.LBB0_1220:
	s_or_b64 exec, exec, s[14:15]
	v_lshl_or_b32 v38, s4, 5, v8
	v_lshl_or_b32 v22, s6, 14, v28
	v_mov_b32_e32 v23, v11
	v_ashrrev_i32_e32 v39, 31, v38
	v_lshl_add_u64 v[46:47], v[22:23], 0, v[38:39]
	v_lshl_add_u64 v[22:23], v[46:47], 1, s[8:9]
	v_readlane_b32 s36, v252, 30
	v_readlane_b32 s50, v252, 44
	v_readlane_b32 s51, v252, 45
	v_add_f32_e32 v19, 0, v19
	v_add_f32_e32 v19, v19, v20
	v_lshl_add_u64 v[48:49], v[38:39], 2, s[50:51]
	v_add_f32_e32 v19, v19, v31
	v_add_f32_e32 v19, v19, v32
	v_add_f32_e32 v19, v19, v33
	v_add_f32_e32 v19, v19, v34
	v_add_f32_e32 v19, v19, v35
	v_add_f32_e32 v19, v19, v36
	ds_bpermute_b32 v20, v26, v19
	v_readlane_b32 s37, v252, 31
	v_readlane_b32 s38, v252, 32
	v_readlane_b32 s39, v252, 33
	v_readlane_b32 s40, v252, 34
	s_waitcnt lgkmcnt(0)
	v_add_f32_e32 v19, v19, v20
	ds_bpermute_b32 v20, v27, v19
	v_readlane_b32 s41, v252, 35
	v_readlane_b32 s42, v252, 36
	v_readlane_b32 s43, v252, 37
	v_readlane_b32 s36, v252, 0
	s_waitcnt lgkmcnt(0)
	v_add_f32_e32 v19, v19, v20
	v_fmamk_f32 v19, v19, 0x3a800000, v29
	v_mul_f32_e32 v20, 0x4f800000, v19
	v_cmp_gt_f32_e32 vcc, s28, v19
	v_readlane_b32 s40, v252, 4
	v_readlane_b32 s41, v252, 5
	v_cndmask_b32_e32 v19, v19, v20, vcc
	v_sqrt_f32_e32 v20, v19
	v_readlane_b32 s44, v252, 38
	v_readlane_b32 s45, v252, 39
	v_readlane_b32 s46, v252, 40
	v_add_u32_e32 v26, -1, v20
	v_add_u32_e32 v27, 1, v20
	v_fma_f32 v31, -v26, v20, v19
	v_fma_f32 v32, -v27, v20, v19
	v_cmp_ge_f32_e64 s[4:5], 0, v31
	v_readlane_b32 s47, v252, 41
	v_readlane_b32 s48, v252, 42
	v_cndmask_b32_e64 v20, v20, v26, s[4:5]
	v_cmp_lt_f32_e64 s[4:5], 0, v32
	v_readlane_b32 s49, v252, 43
	v_readlane_b32 s37, v252, 1
	v_cndmask_b32_e64 v20, v20, v27, s[4:5]
	v_mul_f32_e32 v26, 0x37800000, v20
	v_cndmask_b32_e32 v20, v20, v26, vcc
	v_cmp_class_f32_e32 vcc, v19, v30
	v_lshl_add_u64 v[26:27], v[46:47], 2, s[40:41]
	v_readlane_b32 s38, v252, 2
	v_cndmask_b32_e32 v19, v20, v19, vcc
	v_div_scale_f32 v20, s[4:5], v19, v19, 1.0
	v_rcp_f32_e32 v31, v20
	v_div_scale_f32 v32, vcc, 1.0, v19, 1.0
	v_readlane_b32 s39, v252, 3
	v_fma_f32 v33, -v20, v31, 1.0
	v_fmac_f32_e32 v31, v33, v31
	v_mul_f32_e32 v33, v32, v31
	v_fma_f32 v34, -v20, v33, v32
	v_fmac_f32_e32 v33, v34, v31
	v_fma_f32 v20, -v20, v33, v32
	v_div_fmas_f32 v20, v20, v31, v33
	v_div_fixup_f32 v20, v20, v19, 1.0
	v_pk_mul_f32 v[6:7], v[6:7], v[20:21] op_sel_hi:[1,0]
	v_pk_mul_f32 v[4:5], v[4:5], v[20:21] op_sel_hi:[1,0]
	v_pk_mul_f32 v[32:33], v[2:3], v[20:21] op_sel_hi:[1,0]
	v_pk_mul_f32 v[34:35], v[0:1], v[20:21] op_sel_hi:[1,0]
	v_readlane_b32 s42, v252, 6
	v_readlane_b32 s43, v252, 7
	s_waitcnt vmcnt(0)
	v_lshlrev_b32_e32 v0, 16, v220
	v_and_b32_e32 v1, 0xffff0000, v220
	v_lshlrev_b32_e32 v2, 16, v221
	v_and_b32_e32 v3, 0xffff0000, v221
	v_lshlrev_b32_e32 v22, 16, v222
	v_and_b32_e32 v23, 0xffff0000, v222
	v_lshlrev_b32_e32 v24, 16, v223
	v_and_b32_e32 v25, 0xffff0000, v223
	s_waitcnt vmcnt(1)
	v_pk_fma_f32 v[2:3], v[226:227], v[4:5], v[2:3]
	v_pk_fma_f32 v[0:1], v[224:225], v[6:7], v[0:1]
	s_waitcnt vmcnt(0)
	v_pk_fma_f32 v[6:7], v[230:231], v[34:35], v[24:25]
	v_pk_fma_f32 v[4:5], v[228:229], v[32:33], v[22:23]
	global_store_dwordx4 v[26:27], v[0:3], off
	global_store_dwordx4 v[26:27], v[4:7], off offset:16

.LBB0_1227:
	s_or_b64 exec, exec, s[16:17]
	v_lshl_or_b32 v236, s4, 5, v8
	v_lshl_or_b32 v238, s6, 14, v28
	v_mov_b32_e32 v239, v11
	v_ashrrev_i32_e32 v237, 31, v236
	v_lshl_add_u64 v[240:241], v[238:239], 0, v[236:237]
	v_lshl_add_u64 v[240:241], v[240:241], 1, s[8:9]
	v_readlane_b32 s50, v252, 44
	v_readlane_b32 s51, v252, 45
	s_nop 1
	v_lshl_add_u64 v[242:243], v[236:237], 2, s[50:51]
	global_load_dwordx4 v[220:223], v[240:241], off
	global_load_dwordx4 v[224:227], v[242:243], off
	global_load_dwordx4 v[228:231], v[242:243], off offset:16
	v_lshl_add_u64 v[22:23], s[14:15], 0, v[10:11]
	v_lshlrev_b32_e32 v24, 3, v8
	v_mov_b32_e32 v25, v11
	v_lshl_add_u64 v[22:23], v[22:23], 0, v[24:25]
	s_waitcnt lgkmcnt(0)
	v_mov_b32_e32 v20, 0
	s_mov_b64 s[14:15], 0
	s_branch .LBB0_1230
